# LayerNorm row reductions: first four butterfly steps via DPP adds instead of ds_bpermute round trips (on top of v20)
# speedup vs baseline: 1.0008x; 1.0008x over previous
; __device__ __forceinline__ void ln_phase(const Params& P, const float* g, const float* b, bf16_t* xb) {
;     const int lane = threadIdx.x & 63;
;     const int gw = blockIdx.x * 8 + (threadIdx.x >> 6), nw = gridDim.x * 8;
;     for (int row = gw; row < NTOK; row += nw) {
;         float* y = P.out + O_Y + (size_t)row * 2048;
;         float4 v[8]; float s = 0.f;
; #pragma unroll
;         for (int i = 0; i < 8; ++i) { v[i] = *(const float4*)(y + (i * 64 + lane) * 4); s += (v[i].x + v[i].y) + (v[i].z + v[i].w); }
;         s = halfsum32(s); s += __shfl_xor(s, 32);
.LBB0_2651:
	global_load_dwordx4 v[0:3], v[26:27], off offset:2048
	global_load_dwordx4 v[28:31], v[26:27], off offset:1024
	global_load_dwordx4 v[32:35], v[26:27], off offset:-1024
	global_load_dwordx4 v[36:39], v[26:27], off offset:-2048
	global_load_dwordx4 v[40:43], v[26:27], off offset:-4096
	global_load_dwordx4 v[44:47], v[26:27], off offset:-3072
	global_load_dwordx4 v[66:69], v[26:27], off
	global_load_dwordx4 v[70:73], v[26:27], off offset:3072
	s_waitcnt vmcnt(7)
	v_mov_b32_e32 v48, v1
	s_waitcnt vmcnt(6)
	v_mov_b32_e32 v52, v28
	v_mov_b32_e32 v53, v30
	v_mov_b32_e32 v54, v29
	v_mov_b32_e32 v55, v31
	s_waitcnt vmcnt(5)
	v_mov_b32_e32 v56, v33
	v_mov_b32_e32 v74, v35
	s_waitcnt vmcnt(4)
	v_mov_b32_e32 v76, v36
	v_mov_b32_e32 v77, v38
	v_mov_b32_e32 v78, v37
	v_mov_b32_e32 v79, v39
	s_waitcnt vmcnt(3)
	v_mov_b32_e32 v80, v40
	s_waitcnt vmcnt(2)
	v_mov_b32_e32 v81, v44
	v_mov_b32_e32 v82, v41
	v_mov_b32_e32 v83, v45
	v_mov_b32_e32 v84, v42
	v_mov_b32_e32 v85, v46
	v_mov_b32_e32 v86, v43
	v_mov_b32_e32 v87, v47
	v_pk_add_f32 v[52:53], v[52:53], v[54:55]
	v_pk_add_f32 v[54:55], v[32:33], v[56:57]
	v_pk_add_f32 v[56:57], v[34:35], v[74:75]
	v_pk_add_f32 v[74:75], v[76:77], v[78:79]
	v_pk_add_f32 v[76:77], v[80:81], v[82:83]
	v_pk_add_f32 v[78:79], v[84:85], v[86:87]
	s_waitcnt vmcnt(1)
	v_mov_b32_e32 v49, v66
	v_pk_add_f32 v[76:77], v[76:77], v[78:79]
	v_pk_add_f32 v[88:89], v[0:1], v[48:49]
	v_pk_add_f32 v[74:75], v[74:75], v[74:75] op_sel:[0,1] op_sel_hi:[1,0]
	v_add_f32_e32 v48, 0, v76
	v_mov_b32_e32 v55, v68
	v_mov_b32_e32 v57, v69
	v_mov_b32_e32 v75, v67
	v_add_f32_e32 v48, v48, v77
	v_pk_add_f32 v[54:55], v[54:55], v[56:57]
	v_pk_add_f32 v[48:49], v[48:49], v[74:75]
	v_mov_b32_e32 v50, v3
	v_pk_add_f32 v[48:49], v[48:49], v[54:55]
	v_pk_add_f32 v[50:51], v[2:3], v[50:51]
	v_pk_add_f32 v[52:53], v[52:53], v[52:53] op_sel:[0,1] op_sel_hi:[1,0]
	v_pk_add_f32 v[48:49], v[48:49], v[48:49] op_sel:[0,1] op_sel_hi:[1,0]
	s_waitcnt vmcnt(0)
	v_mov_b32_e32 v89, v72
	v_mov_b32_e32 v51, v73
	v_mov_b32_e32 v53, v71
	v_mov_b32_e32 v49, v70
	v_pk_add_f32 v[50:51], v[88:89], v[50:51]
	v_pk_add_f32 v[48:49], v[48:49], v[52:53]
	global_load_dwordx4 v[74:77], v[4:5], off
	global_load_dwordx4 v[78:81], v[6:7], off
	v_pk_add_f32 v[48:49], v[48:49], v[50:51]
	s_nop 0
	v_add_f32_e32 v48, v48, v49
	s_nop 1
	v_add_f32_dpp v48, v48, v48 quad_perm:[1,0,3,2] row_mask:0xf bank_mask:0xf
	s_nop 1
	v_add_f32_dpp v48, v48, v48 quad_perm:[2,3,0,1] row_mask:0xf bank_mask:0xf
	s_nop 1
	v_add_f32_dpp v48, v48, v48 row_half_mirror row_mask:0xf bank_mask:0xf
	s_nop 1
	v_add_f32_dpp v48, v48, v48 row_mirror row_mask:0xf bank_mask:0xf
	ds_bpermute_b32 v49, v62, v48
	s_waitcnt lgkmcnt(0)
	v_add_f32_e32 v48, v48, v49
	ds_bpermute_b32 v49, v63, v48
	s_waitcnt lgkmcnt(0)
; __device__ __forceinline__ unsigned pk_bf16(float lo, float hi) { unsigned r; asm("v_cvt_pk_bf16_f32 %0, %1, %2" : "=v"(r) : "v"(lo), "v"(hi)); return r; }
; __device__ __forceinline__ void ln_phase(const Params& P, const float* g, const float* b, bf16_t* xb) {
;     ...
;         const float mu = s * (1.0f / 2048.0f); float q = 0.f;
; #pragma unroll
;         for (int i = 0; i < 8; ++i) { v[i].x -= mu; v[i].y -= mu; v[i].z -= mu; v[i].w -= mu; q += (v[i].x * v[i].x + v[i].y * v[i].y) + (v[i].z * v[i].z + v[i].w * v[i].w); }
;         q = halfsum32(q); q += __shfl_xor(q, 32);
;         const float rstd = rsqrtf(q * (1.0f / 2048.0f) + 1e-5f);
; #pragma unroll
;         for (int i = 0; i < 8; ++i) { const int c = (i * 64 + lane) * 4; const float4 gg = *(const float4*)(g + c), bb = *(const float4*)(b + c);
;             float4 o; o.x = v[i].x * rstd * gg.x + bb.x; o.y = v[i].y * rstd * gg.y + bb.y; o.z = v[i].z * rstd * gg.z + bb.z; o.w = v[i].w * rstd * gg.w + bb.w;
;             *(float4*)(y + c) = o;
;             if (xb) { uint2 w; w.x = pk_bf16(o.x, o.y); w.y = pk_bf16(o.z, o.w); *(uint2*)(xb + (size_t)row * 2048 + c) = w; } }
	v_add_f32_e32 v48, v48, v49
	v_mul_f32_e32 v48, 0x3a000000, v48
	v_pk_add_f32 v[82:83], v[40:41], v[48:49] op_sel_hi:[1,0] neg_lo:[0,1] neg_hi:[0,1]
	v_pk_add_f32 v[84:85], v[42:43], v[48:49] op_sel_hi:[1,0] neg_lo:[0,1] neg_hi:[0,1]
	v_pk_add_f32 v[54:55], v[44:45], v[48:49] op_sel_hi:[1,0] neg_lo:[0,1] neg_hi:[0,1]
	v_pk_add_f32 v[56:57], v[46:47], v[48:49] op_sel_hi:[1,0] neg_lo:[0,1] neg_hi:[0,1]
	v_pk_add_f32 v[50:51], v[36:37], v[48:49] op_sel_hi:[1,0] neg_lo:[0,1] neg_hi:[0,1]
	v_pk_add_f32 v[52:53], v[38:39], v[48:49] op_sel_hi:[1,0] neg_lo:[0,1] neg_hi:[0,1]
	v_pk_add_f32 v[46:47], v[34:35], v[48:49] op_sel_hi:[1,0] neg_lo:[0,1] neg_hi:[0,1]
	v_pk_add_f32 v[40:41], v[66:67], v[48:49] op_sel_hi:[1,0] neg_lo:[0,1] neg_hi:[0,1]
	v_pk_add_f32 v[34:35], v[2:3], v[48:49] op_sel_hi:[1,0] neg_lo:[0,1] neg_hi:[0,1]
	v_mov_b32_e32 v2, v83
	v_mov_b32_e32 v3, v55
	v_mov_b32_e32 v66, v85
	v_mov_b32_e32 v67, v57
	v_pk_add_f32 v[44:45], v[32:33], v[48:49] op_sel_hi:[1,0] neg_lo:[0,1] neg_hi:[0,1]
	v_pk_add_f32 v[42:43], v[68:69], v[48:49] op_sel_hi:[1,0] neg_lo:[0,1] neg_hi:[0,1]
	v_pk_add_f32 v[36:37], v[28:29], v[48:49] op_sel_hi:[1,0] neg_lo:[0,1] neg_hi:[0,1]
	v_pk_add_f32 v[38:39], v[30:31], v[48:49] op_sel_hi:[1,0] neg_lo:[0,1] neg_hi:[0,1]
	v_pk_add_f32 v[32:33], v[0:1], v[48:49] op_sel_hi:[1,0] neg_lo:[0,1] neg_hi:[0,1]
	v_pk_add_f32 v[28:29], v[70:71], v[48:49] op_sel_hi:[1,0] neg_lo:[0,1] neg_hi:[0,1]
	v_pk_add_f32 v[30:31], v[72:73], v[48:49] op_sel_hi:[1,0] neg_lo:[0,1] neg_hi:[0,1]
	v_mov_b32_e32 v0, v82
	v_mov_b32_e32 v1, v54
	v_mov_b32_e32 v48, v84
	v_mov_b32_e32 v49, v56
	v_mov_b32_e32 v70, v51
	v_mov_b32_e32 v71, v53
	v_pk_mul_f32 v[2:3], v[2:3], v[2:3]
	v_pk_mul_f32 v[66:67], v[66:67], v[66:67]
	v_mov_b32_e32 v68, v50
	v_mov_b32_e32 v69, v52
	v_pk_mul_f32 v[70:71], v[70:71], v[70:71]
	v_pk_fma_f32 v[0:1], v[0:1], v[0:1], v[2:3]
	v_pk_fma_f32 v[2:3], v[48:49], v[48:49], v[66:67]
	v_mul_f32_e32 v72, v44, v44
	v_mul_f32_e32 v86, v46, v46
	v_pk_fma_f32 v[48:49], v[68:69], v[68:69], v[70:71]
	v_pk_add_f32 v[0:1], v[0:1], v[2:3]
	v_pk_mul_f32 v[88:89], v[40:41], v[40:41]
	v_pk_mul_f32 v[90:91], v[42:43], v[42:43]
	v_pk_fma_f32 v[72:73], v[44:45], v[44:45], v[72:73] op_sel_hi:[1,1,0]
	v_pk_fma_f32 v[86:87], v[46:47], v[46:47], v[86:87] op_sel_hi:[1,1,0]
	v_pk_add_f32 v[2:3], v[48:49], v[48:49] op_sel_hi:[0,1]
	v_pk_add_f32 v[0:1], v[0:1], v[0:1] op_sel_hi:[0,1]
	v_mov_b32_e32 v94, v37
	v_mov_b32_e32 v95, v39
	v_mov_b32_e32 v72, v88
	v_mov_b32_e32 v86, v89
	v_mov_b32_e32 v2, v90
	v_mov_b32_e32 v0, v91
	v_mov_b32_e32 v92, v36
	v_mov_b32_e32 v93, v38
	v_pk_mul_f32 v[94:95], v[94:95], v[94:95]
	v_pk_add_f32 v[48:49], v[72:73], v[86:87]
	v_pk_add_f32 v[0:1], v[2:3], v[0:1]
	v_mul_f32_e32 v96, v32, v32
	v_mul_f32_e32 v98, v34, v34
	v_pk_fma_f32 v[66:67], v[92:93], v[92:93], v[94:95]
	v_pk_add_f32 v[0:1], v[48:49], v[0:1]
	v_pk_mul_f32 v[100:101], v[28:29], v[28:29]
	v_pk_mul_f32 v[102:103], v[30:31], v[30:31]
	v_pk_fma_f32 v[96:97], v[32:33], v[32:33], v[96:97] op_sel_hi:[1,1,0]
	v_pk_fma_f32 v[98:99], v[34:35], v[34:35], v[98:99] op_sel_hi:[1,1,0]
	v_pk_add_f32 v[66:67], v[66:67], v[66:67] op_sel_hi:[0,1]
	v_pk_add_f32 v[0:1], v[0:1], v[0:1] op_sel_hi:[0,1]
	v_mov_b32_e32 v96, v100
	v_mov_b32_e32 v98, v101
	v_mov_b32_e32 v66, v102
	v_mov_b32_e32 v0, v103
	v_pk_add_f32 v[68:69], v[96:97], v[98:99]
	v_pk_add_f32 v[0:1], v[66:67], v[0:1]
	s_nop 0
	v_pk_add_f32 v[0:1], v[68:69], v[0:1]
	s_nop 0
	v_add_f32_e32 v0, v0, v1
	s_nop 1
	v_add_f32_dpp v0, v0, v0 quad_perm:[1,0,3,2] row_mask:0xf bank_mask:0xf
	s_nop 1
	v_add_f32_dpp v0, v0, v0 quad_perm:[2,3,0,1] row_mask:0xf bank_mask:0xf
	s_nop 1
	v_add_f32_dpp v0, v0, v0 row_half_mirror row_mask:0xf bank_mask:0xf
	s_nop 1
	v_add_f32_dpp v0, v0, v0 row_mirror row_mask:0xf bank_mask:0xf
	ds_bpermute_b32 v1, v62, v0
	s_waitcnt lgkmcnt(0)
	v_add_f32_e32 v0, v0, v1
	ds_bpermute_b32 v1, v63, v0
	s_waitcnt lgkmcnt(0)
	v_add_f32_e32 v0, v0, v1
	v_fmamk_f32 v0, v0, 0x3a000000, v64
	v_mul_f32_e32 v1, 0x4b800000, v0
	v_cmp_gt_f32_e32 vcc, s1, v0
	s_nop 1
	v_cndmask_b32_e32 v0, v0, v1, vcc
	v_rsq_f32_e32 v0, v0
	v_cndmask_b32_e64 v1, 0, 1, s[52:53]
	v_cmp_ne_u32_e64 s[6:7], 1, v1
	v_mul_f32_e32 v1, 0x45800000, v0
	v_cndmask_b32_e32 v48, v0, v1, vcc
	v_pk_mul_f32 v[0:1], v[82:83], v[48:49] op_sel_hi:[1,0]
	v_pk_mul_f32 v[2:3], v[84:85], v[48:49] op_sel_hi:[1,0]
	s_waitcnt vmcnt(0)
	v_pk_fma_f32 v[0:1], v[74:75], v[0:1], v[78:79]
	v_pk_fma_f32 v[2:3], v[76:77], v[2:3], v[80:81]
	s_andn2_b64 vcc, exec, s[52:53]
	global_store_dwordx4 v[26:27], v[0:3], off offset:-4096
	s_cbranch_vccnz .LBB0_2653
	s_nop 0
	v_cvt_pk_bf16_f32 v0, v0, v1
	v_cvt_pk_bf16_f32 v1, v2, v3
	global_store_dwordx2 v[24:25], v[0:1], off offset:-3588

; __device__ __forceinline__ void ln_phase(const Params& P, const float* g, const float* b, bf16_t* xb) {
;     ...
;     for (int row = gw; row < NTOK; row += nw) {
;         float* y = P.out + O_Y + (size_t)row * 2048;
;         float4 v[8]; float s = 0.f;
; #pragma unroll
;         for (int i = 0; i < 8; ++i) { v[i] = *(const float4*)(y + (i * 64 + lane) * 4); s += (v[i].x + v[i].y) + (v[i].z + v[i].w); }
;         s = halfsum32(s); s += __shfl_xor(s, 32);
;         const float mu = s * (1.0f / 2048.0f); float q = 0.f;
; #pragma unroll
;         for (int i = 0; i < 8; ++i) { v[i].x -= mu; v[i].y -= mu; v[i].z -= mu; v[i].w -= mu; q += (v[i].x * v[i].x + v[i].y * v[i].y) + (v[i].z * v[i].z + v[i].w * v[i].w); }
;         q = halfsum32(q); q += __shfl_xor(q, 32);
.LBB0_2837:
	global_load_dwordx4 v[30:33], v[20:21], off offset:-4096
	global_load_dwordx4 v[34:37], v[20:21], off offset:-3072
	global_load_dwordx4 v[38:41], v[20:21], off offset:-2048
	global_load_dwordx4 v[42:45], v[20:21], off offset:-1024
	global_load_dwordx4 v[46:49], v[20:21], off
	global_load_dwordx4 v[50:53], v[20:21], off offset:1024
	global_load_dwordx4 v[54:57], v[20:21], off offset:2048
	global_load_dwordx4 v[58:61], v[20:21], off offset:3072
	v_add_u32_e32 v124, s0, v124
	s_waitcnt vmcnt(7)
	v_mov_b32_e32 v62, v30
	s_waitcnt vmcnt(6)
	v_mov_b32_e32 v63, v34
	v_mov_b32_e32 v64, v31
	v_mov_b32_e32 v65, v35
	v_mov_b32_e32 v66, v32
	v_mov_b32_e32 v67, v36
	v_mov_b32_e32 v68, v33
	v_mov_b32_e32 v69, v37
	s_waitcnt vmcnt(5)
	v_mov_b32_e32 v70, v38
	v_mov_b32_e32 v71, v40
	v_mov_b32_e32 v72, v39
	v_mov_b32_e32 v73, v41
	v_pk_add_f32 v[62:63], v[62:63], v[64:65]
	v_pk_add_f32 v[64:65], v[66:67], v[68:69]
	s_waitcnt vmcnt(4)
	v_mov_b32_e32 v74, v43
	v_mov_b32_e32 v76, v45
	s_waitcnt vmcnt(3)
	v_mov_b32_e32 v75, v46
	v_pk_add_f32 v[66:67], v[70:71], v[72:73]
	v_pk_add_f32 v[62:63], v[62:63], v[64:65]
	v_pk_add_f32 v[68:69], v[42:43], v[74:75]
	v_pk_add_f32 v[70:71], v[44:45], v[76:77]
	v_pk_add_f32 v[64:65], v[66:67], v[66:67] op_sel:[0,1] op_sel_hi:[1,0]
	v_add_f32_e32 v29, 0, v62
	v_mov_b32_e32 v69, v48
	v_mov_b32_e32 v71, v49
	v_mov_b32_e32 v65, v47
	v_add_f32_e32 v74, v29, v63
	s_waitcnt vmcnt(2)
	v_mov_b32_e32 v78, v50
	v_mov_b32_e32 v79, v52
	v_mov_b32_e32 v80, v51
	v_mov_b32_e32 v81, v53
	v_pk_add_f32 v[68:69], v[68:69], v[70:71]
	v_pk_add_f32 v[62:63], v[74:75], v[64:65]
	s_waitcnt vmcnt(1)
	v_mov_b32_e32 v82, v55
	v_mov_b32_e32 v84, v57
	v_pk_add_f32 v[72:73], v[78:79], v[80:81]
	v_pk_add_f32 v[62:63], v[62:63], v[68:69]
	v_pk_add_f32 v[76:77], v[54:55], v[82:83]
	v_pk_add_f32 v[78:79], v[56:57], v[84:85]
	v_pk_add_f32 v[66:67], v[72:73], v[72:73] op_sel:[0,1] op_sel_hi:[1,0]
	v_pk_add_f32 v[62:63], v[62:63], v[62:63] op_sel:[0,1] op_sel_hi:[1,0]
	s_waitcnt vmcnt(0)
	v_mov_b32_e32 v77, v60
	v_mov_b32_e32 v79, v61
	v_mov_b32_e32 v67, v59
	v_mov_b32_e32 v63, v58
	v_pk_add_f32 v[70:71], v[76:77], v[78:79]
	v_pk_add_f32 v[62:63], v[62:63], v[66:67]
	s_nop 0
	v_pk_add_f32 v[62:63], v[62:63], v[70:71]
	s_nop 0
	v_add_f32_e32 v29, v62, v63
	s_nop 1
	v_add_f32_dpp v29, v29, v29 quad_perm:[1,0,3,2] row_mask:0xf bank_mask:0xf
	s_nop 1
	v_add_f32_dpp v29, v29, v29 quad_perm:[2,3,0,1] row_mask:0xf bank_mask:0xf
	s_nop 1
	v_add_f32_dpp v29, v29, v29 row_half_mirror row_mask:0xf bank_mask:0xf
	s_nop 1
	v_add_f32_dpp v29, v29, v29 row_mirror row_mask:0xf bank_mask:0xf
	ds_bpermute_b32 v62, v26, v29
	s_waitcnt lgkmcnt(0)
	v_add_f32_e32 v29, v29, v62
	s_nop 1
	v_mov_b64_e32 v[62:63], v[150:151]
	v_mov_b64_e32 v[64:65], v[152:153]
	s_nop 1
	v_mov_b64_e32 v[66:67], v[154:155]
	v_mov_b64_e32 v[68:69], v[156:157]
	ds_bpermute_b32 v70, v27, v29
	s_waitcnt lgkmcnt(0)
	v_add_f32_e32 v29, v29, v70
	v_mul_f32_e32 v70, 0x3a000000, v29
	v_pk_add_f32 v[30:31], v[30:31], v[70:71] op_sel_hi:[1,0] neg_lo:[0,1] neg_hi:[0,1]
	v_pk_add_f32 v[32:33], v[32:33], v[70:71] op_sel_hi:[1,0] neg_lo:[0,1] neg_hi:[0,1]
	v_pk_add_f32 v[72:73], v[34:35], v[70:71] op_sel_hi:[1,0] neg_lo:[0,1] neg_hi:[0,1]
	v_pk_add_f32 v[74:75], v[36:37], v[70:71] op_sel_hi:[1,0] neg_lo:[0,1] neg_hi:[0,1]
	v_pk_add_f32 v[38:39], v[38:39], v[70:71] op_sel_hi:[1,0] neg_lo:[0,1] neg_hi:[0,1]
	v_pk_add_f32 v[40:41], v[40:41], v[70:71] op_sel_hi:[1,0] neg_lo:[0,1] neg_hi:[0,1]
	v_mov_b32_e32 v36, v31
	v_mov_b32_e32 v37, v73
	v_mov_b32_e32 v76, v33
	v_mov_b32_e32 v77, v75
	v_pk_add_f32 v[42:43], v[42:43], v[70:71] op_sel_hi:[1,0] neg_lo:[0,1] neg_hi:[0,1]
	v_pk_add_f32 v[44:45], v[44:45], v[70:71] op_sel_hi:[1,0] neg_lo:[0,1] neg_hi:[0,1]
	v_pk_add_f32 v[46:47], v[46:47], v[70:71] op_sel_hi:[1,0] neg_lo:[0,1] neg_hi:[0,1]
	v_pk_add_f32 v[48:49], v[48:49], v[70:71] op_sel_hi:[1,0] neg_lo:[0,1] neg_hi:[0,1]
	v_pk_add_f32 v[50:51], v[50:51], v[70:71] op_sel_hi:[1,0] neg_lo:[0,1] neg_hi:[0,1]
	v_pk_add_f32 v[52:53], v[52:53], v[70:71] op_sel_hi:[1,0] neg_lo:[0,1] neg_hi:[0,1]
	v_pk_add_f32 v[54:55], v[54:55], v[70:71] op_sel_hi:[1,0] neg_lo:[0,1] neg_hi:[0,1]
	v_pk_add_f32 v[56:57], v[56:57], v[70:71] op_sel_hi:[1,0] neg_lo:[0,1] neg_hi:[0,1]
	v_pk_add_f32 v[58:59], v[58:59], v[70:71] op_sel_hi:[1,0] neg_lo:[0,1] neg_hi:[0,1]
	v_pk_add_f32 v[60:61], v[60:61], v[70:71] op_sel_hi:[1,0] neg_lo:[0,1] neg_hi:[0,1]
	v_mov_b32_e32 v34, v30
	v_mov_b32_e32 v35, v72
	v_mov_b32_e32 v70, v32
	v_mov_b32_e32 v71, v74
	v_mov_b32_e32 v80, v39
	v_mov_b32_e32 v81, v41
	v_pk_mul_f32 v[36:37], v[36:37], v[36:37]
	v_pk_mul_f32 v[76:77], v[76:77], v[76:77]
	v_mov_b32_e32 v78, v38
	v_mov_b32_e32 v79, v40
	v_pk_mul_f32 v[80:81], v[80:81], v[80:81]
	v_pk_fma_f32 v[34:35], v[34:35], v[34:35], v[36:37]
	v_pk_fma_f32 v[36:37], v[70:71], v[70:71], v[76:77]
	v_mul_f32_e32 v82, v42, v42
	v_mul_f32_e32 v84, v44, v44
	v_pk_fma_f32 v[70:71], v[78:79], v[78:79], v[80:81]
	v_pk_add_f32 v[34:35], v[34:35], v[36:37]
	v_pk_mul_f32 v[86:87], v[46:47], v[46:47]
	v_pk_mul_f32 v[88:89], v[48:49], v[48:49]
	v_pk_fma_f32 v[82:83], v[42:43], v[42:43], v[82:83] op_sel_hi:[1,1,0]
	v_pk_fma_f32 v[84:85], v[44:45], v[44:45], v[84:85] op_sel_hi:[1,1,0]
	v_pk_add_f32 v[36:37], v[70:71], v[70:71] op_sel_hi:[0,1]
	v_pk_add_f32 v[34:35], v[34:35], v[34:35] op_sel_hi:[0,1]
	v_mov_b32_e32 v92, v51
	v_mov_b32_e32 v93, v53
	v_mov_b32_e32 v82, v86
	v_mov_b32_e32 v84, v87
	v_mov_b32_e32 v36, v88
	v_mov_b32_e32 v34, v89
	v_mov_b32_e32 v90, v50
	v_mov_b32_e32 v91, v52
	v_pk_mul_f32 v[92:93], v[92:93], v[92:93]
	v_pk_add_f32 v[70:71], v[82:83], v[84:85]
	v_pk_add_f32 v[34:35], v[36:37], v[34:35]
	v_mul_f32_e32 v94, v54, v54
	v_mul_f32_e32 v96, v56, v56
	v_pk_fma_f32 v[76:77], v[90:91], v[90:91], v[92:93]
	v_pk_add_f32 v[34:35], v[70:71], v[34:35]
	v_pk_mul_f32 v[98:99], v[58:59], v[58:59]
	v_pk_mul_f32 v[100:101], v[60:61], v[60:61]
	v_pk_fma_f32 v[94:95], v[54:55], v[54:55], v[94:95] op_sel_hi:[1,1,0]
	v_pk_fma_f32 v[96:97], v[56:57], v[56:57], v[96:97] op_sel_hi:[1,1,0]
	v_pk_add_f32 v[76:77], v[76:77], v[76:77] op_sel_hi:[0,1]
	v_pk_add_f32 v[34:35], v[34:35], v[34:35] op_sel_hi:[0,1]
	v_mov_b32_e32 v94, v98
	v_mov_b32_e32 v96, v99
	v_mov_b32_e32 v76, v100
	v_mov_b32_e32 v34, v101
	v_pk_add_f32 v[78:79], v[94:95], v[96:97]
	v_pk_add_f32 v[34:35], v[76:77], v[34:35]
	s_nop 0
	v_pk_add_f32 v[34:35], v[78:79], v[34:35]
	s_nop 0
	v_add_f32_e32 v29, v34, v35
	s_nop 1
	v_add_f32_dpp v29, v29, v29 quad_perm:[1,0,3,2] row_mask:0xf bank_mask:0xf
	s_nop 1
	v_add_f32_dpp v29, v29, v29 quad_perm:[2,3,0,1] row_mask:0xf bank_mask:0xf
	s_nop 1
	v_add_f32_dpp v29, v29, v29 row_half_mirror row_mask:0xf bank_mask:0xf
	s_nop 1
	v_add_f32_dpp v29, v29, v29 row_mirror row_mask:0xf bank_mask:0xf
	ds_bpermute_b32 v34, v26, v29
	s_waitcnt lgkmcnt(0)
; __device__ __forceinline__ void ln_phase(const Params& P, const float* g, const float* b, bf16_t* xb) {
;     ...
;         const float rstd = rsqrtf(q * (1.0f / 2048.0f) + 1e-5f);
; #pragma unroll
;         for (int i = 0; i < 8; ++i) { const int c = (i * 64 + lane) * 4; const float4 gg = *(const float4*)(g + c), bb = *(const float4*)(b + c);
;             float4 o; o.x = v[i].x * rstd * gg.x + bb.x; o.y = v[i].y * rstd * gg.y + bb.y; o.z = v[i].z * rstd * gg.z + bb.z; o.w = v[i].w * rstd * gg.w + bb.w;
;             *(float4*)(y + c) = o;
	v_add_f32_e32 v29, v29, v34
	ds_bpermute_b32 v34, v27, v29
	s_waitcnt lgkmcnt(0)
	v_add_f32_e32 v29, v29, v34
	v_fmamk_f32 v29, v29, 0x3a000000, v28
	v_mul_f32_e32 v34, 0x4b800000, v29
	v_cmp_gt_f32_e32 vcc, s1, v29
	s_nop 1
	v_cndmask_b32_e32 v29, v29, v34, vcc
	v_rsq_f32_e32 v29, v29
	s_nop 0
	v_mul_f32_e32 v34, 0x45800000, v29
	v_cndmask_b32_e32 v70, v29, v34, vcc
	v_pk_mul_f32 v[30:31], v[30:31], v[70:71] op_sel_hi:[1,0]
	v_pk_mul_f32 v[32:33], v[32:33], v[70:71] op_sel_hi:[1,0]
	v_pk_fma_f32 v[30:31], v[62:63], v[30:31], v[66:67]
	v_pk_fma_f32 v[32:33], v[64:65], v[32:33], v[68:69]
	global_store_dwordx4 v[20:21], v[30:33], off offset:-4096
	s_nop 1
	v_mov_b64_e32 v[30:31], v[158:159]
	v_mov_b64_e32 v[32:33], v[160:161]
	s_nop 0
	s_nop 1
	v_mov_b64_e32 v[34:35], v[162:163]
	v_mov_b64_e32 v[36:37], v[164:165]
	v_pk_mul_f32 v[62:63], v[72:73], v[70:71] op_sel_hi:[1,0]
	v_pk_mul_f32 v[64:65], v[74:75], v[70:71] op_sel_hi:[1,0]
	v_pk_mul_f32 v[38:39], v[38:39], v[70:71] op_sel_hi:[1,0]
	v_pk_mul_f32 v[40:41], v[40:41], v[70:71] op_sel_hi:[1,0]
	v_cmp_lt_i32_e32 vcc, s6, v124
	s_or_b64 s[4:5], vcc, s[4:5]
	v_pk_fma_f32 v[30:31], v[30:31], v[62:63], v[34:35]
	v_pk_fma_f32 v[32:33], v[32:33], v[64:65], v[36:37]
	global_store_dwordx4 v[20:21], v[30:33], off offset:-3072
	s_nop 1
	v_mov_b64_e32 v[30:31], v[166:167]
	v_mov_b64_e32 v[32:33], v[168:169]
	s_nop 0
	s_nop 1
	v_mov_b64_e32 v[34:35], v[170:171]
	v_mov_b64_e32 v[36:37], v[172:173]
	v_pk_fma_f32 v[30:31], v[38:39], v[30:31], v[34:35]
	v_pk_fma_f32 v[32:33], v[40:41], v[32:33], v[36:37]
	global_store_dwordx4 v[20:21], v[30:33], off offset:-2048
	s_nop 1
	v_mov_b64_e32 v[30:31], v[174:175]
	v_mov_b64_e32 v[32:33], v[176:177]
	s_nop 0
	s_nop 1
	v_mov_b64_e32 v[34:35], v[178:179]
	v_mov_b64_e32 v[36:37], v[180:181]
	v_pk_mul_f32 v[38:39], v[42:43], v[70:71] op_sel_hi:[1,0]
	v_pk_mul_f32 v[40:41], v[44:45], v[70:71] op_sel_hi:[1,0]
	v_pk_fma_f32 v[30:31], v[38:39], v[30:31], v[34:35]
	v_pk_fma_f32 v[32:33], v[40:41], v[32:33], v[36:37]
	global_store_dwordx4 v[20:21], v[30:33], off offset:-1024
	s_nop 1
	v_mov_b64_e32 v[30:31], v[182:183]
	v_mov_b64_e32 v[32:33], v[184:185]
	s_nop 0
	s_nop 1
	v_mov_b64_e32 v[34:35], v[186:187]
	v_mov_b64_e32 v[36:37], v[188:189]
	v_pk_mul_f32 v[38:39], v[46:47], v[70:71] op_sel_hi:[1,0]
	v_pk_mul_f32 v[40:41], v[48:49], v[70:71] op_sel_hi:[1,0]
	v_pk_fma_f32 v[30:31], v[38:39], v[30:31], v[34:35]
	v_pk_fma_f32 v[32:33], v[40:41], v[32:33], v[36:37]
	global_store_dwordx4 v[20:21], v[30:33], off
	s_nop 1
	v_mov_b64_e32 v[30:31], v[190:191]
	v_mov_b64_e32 v[32:33], v[192:193]
	s_nop 0
	s_nop 1
	v_mov_b64_e32 v[34:35], v[194:195]
	v_mov_b64_e32 v[36:37], v[196:197]
	v_pk_mul_f32 v[38:39], v[50:51], v[70:71] op_sel_hi:[1,0]
	v_pk_mul_f32 v[40:41], v[52:53], v[70:71] op_sel_hi:[1,0]
	v_pk_fma_f32 v[30:31], v[38:39], v[30:31], v[34:35]
	v_pk_fma_f32 v[32:33], v[40:41], v[32:33], v[36:37]
	global_store_dwordx4 v[20:21], v[30:33], off offset:1024
	s_nop 1
	v_mov_b64_e32 v[30:31], v[198:199]
	v_mov_b64_e32 v[32:33], v[200:201]
	s_nop 0
	s_nop 1
	v_mov_b64_e32 v[34:35], v[202:203]
	v_mov_b64_e32 v[36:37], v[204:205]
	v_pk_mul_f32 v[38:39], v[54:55], v[70:71] op_sel_hi:[1,0]
	v_pk_mul_f32 v[40:41], v[56:57], v[70:71] op_sel_hi:[1,0]
	v_pk_fma_f32 v[30:31], v[38:39], v[30:31], v[34:35]
	v_pk_fma_f32 v[32:33], v[40:41], v[32:33], v[36:37]
	global_store_dwordx4 v[20:21], v[30:33], off offset:2048
	s_nop 1
	v_mov_b64_e32 v[30:31], v[206:207]
	v_mov_b64_e32 v[32:33], v[208:209]
	s_nop 0
	s_nop 1
	v_mov_b64_e32 v[34:35], v[210:211]
	v_mov_b64_e32 v[36:37], v[212:213]
	v_pk_mul_f32 v[38:39], v[58:59], v[70:71] op_sel_hi:[1,0]
	v_pk_mul_f32 v[40:41], v[60:61], v[70:71] op_sel_hi:[1,0]
	v_pk_fma_f32 v[30:31], v[38:39], v[30:31], v[34:35]
	v_pk_fma_f32 v[32:33], v[40:41], v[32:33], v[36:37]
	global_store_dwordx4 v[20:21], v[30:33], off offset:3072
	v_lshl_add_u64 v[20:21], v[20:21], 0, s[2:3]
	s_andn2_b64 exec, exec, s[4:5]
	s_cbranch_execnz .LBB0_2837
